# v54 + mLSTM pre-pass A: all-valid fast path for conv masks and prefetch wait moved to first consumer
# baseline (speedup 1.0000x reference)
; __device__ __forceinline__ bf16_t f2bf(float f) { return (bf16_t)(pk2(f, 0.f) & 0xffffu); }
; __device__ __forceinline__ float bf2f(unsigned short h) { return __uint_as_float(((unsigned)h) << 16); }
; __device__ __forceinline__ float silu_f(float x) { return x * fast_rcp(1.0f + fast_exp(-x)); }
; __device__ __forceinline__ void mlstm_unit(const Params& p, int l, int b, int h, LAS unsigned char* lds) {
;     ...
;         unsigned short qa_[12], ka_[12], qb_[12], kb_[12]; unsigned ma_ = 0u, mb_ = 0u;
;         PP_LOAD(wave, qa_, ka_, ma_);
;         for (int gi = wave; gi < TK / 8; gi += 8) {
;             const int tau0 = gi * 8;
;             if (gi + 8 < TK / 8) PP_LOAD(gi + 8, qb_, kb_, mb_);
;             float qf[12], kf[12];
; #pragma unroll
;             for (int i = 0; i < 12; ++i) { const bool ok = (ma_ >> i) & 1u; qf[i] = ok ? bf2f(qa_[i]) : 0.f; kf[i] = ok ? bf2f(ka_[i]) : 0.f; }
;             float ko[8];
; #pragma unroll
;             for (int i = 0; i < 8; ++i) { float qv = bq, kv = bk;
; #pragma unroll
;                 for (int jj = 0; jj < 5; ++jj) { qv += wq[jj] * qf[i + jj]; kv += wk[jj] * kf[i + jj]; }
;                 const float qo = silu_f(qv) * 0.125f; ko[i] = silu_f(kv);
;                 QA[(size_t)(tau0 + i) * 64 + lane] = f2bf(qo); KA[(size_t)(tau0 + i) * 64 + lane] = f2bf(ko[i]); }
.Lmy_ppfast:
	s_waitcnt vmcnt(24)
	v_lshlrev_b32_e32 v67, 16, v67
	v_lshlrev_b32_e32 v66, 16, v66
	v_lshlrev_b32_e32 v65, 16, v65
	v_lshlrev_b32_e32 v63, 16, v63
	v_lshlrev_b32_e32 v64, 16, v64
	v_lshlrev_b32_e32 v61, 16, v61
	v_lshlrev_b32_e32 v62, 16, v62
	v_lshlrev_b32_e32 v60, 16, v60
	v_mov_b32_e32 v68, v60
	v_lshlrev_b32_e32 v59, 16, v59
	v_lshlrev_b32_e32 v58, 16, v58
	v_mov_b32_e32 v69, v59
	v_mov_b32_e32 v70, v58
	v_lshlrev_b32_e32 v57, 16, v57
	v_lshlrev_b32_e32 v55, 16, v55
	v_mov_b32_e32 v71, v57
	v_mov_b32_e32 v72, v55
	v_lshlrev_b32_e32 v55, 16, v56
	v_lshlrev_b32_e32 v53, 16, v53
	v_mov_b32_e32 v59, v55
	v_mov_b32_e32 v60, v53
	v_lshlrev_b32_e32 v53, 16, v54
	v_lshlrev_b32_e32 v54, 16, v52
	v_mov_b32_e32 v52, v53
	v_mov_b32_e32 v53, v54
	v_lshlrev_b32_e32 v51, 16, v51
	v_lshlrev_b32_e32 v50, 16, v50
	v_lshlrev_b32_e32 v49, 16, v49
	v_lshlrev_b32_e32 v9, 16, v9
	v_mov_b32_e32 v54, v49
	v_mov_b32_e32 v49, v9
	v_lshlrev_b32_e32 v9, 16, v48
	v_lshlrev_b32_e32 v7, 16, v7
	v_mov_b32_e32 v55, v9
	v_mov_b32_e32 v48, v7
	v_lshlrev_b32_e32 v6, 16, v6
	v_mov_b32_e32 v56, v6
	s_mov_b64 s[8:9], 0
	s_branch .Lmy_ppjoin
.LBB0_445:
	s_add_i32 s7, s7, 8
	s_cmp_eq_u32 s28, 0xfff
	s_cbranch_scc1 .Lmy_ppfast
	s_bitcmp0_b32 s28, 0
	s_cselect_b64 s[8:9], -1, 0
	s_waitcnt vmcnt(24)
	v_lshlrev_b32_e32 v67, 16, v67
	v_lshlrev_b32_e32 v66, 16, v66
	s_bitcmp0_b32 s28, 1
	v_cndmask_b32_e64 v67, v67, 0, s[8:9]
	v_cndmask_b32_e64 v66, v66, 0, s[8:9]
	s_cselect_b64 s[8:9], -1, 0
	v_lshlrev_b32_e32 v65, 16, v65
	v_lshlrev_b32_e32 v63, 16, v63
	s_bitcmp0_b32 s28, 2
	v_cndmask_b32_e64 v65, v65, 0, s[8:9]
	v_cndmask_b32_e64 v63, v63, 0, s[8:9]
	s_cselect_b64 s[8:9], -1, 0
	v_lshlrev_b32_e32 v64, 16, v64
	v_lshlrev_b32_e32 v61, 16, v61
	s_bitcmp0_b32 s28, 3
	v_cndmask_b32_e64 v64, v64, 0, s[8:9]
	v_cndmask_b32_e64 v61, v61, 0, s[8:9]
	s_cselect_b64 s[8:9], -1, 0
	v_lshlrev_b32_e32 v62, 16, v62
	v_lshlrev_b32_e32 v60, 16, v60
	s_bitcmp0_b32 s28, 4
	v_cndmask_b32_e64 v62, v62, 0, s[8:9]
	v_cndmask_b32_e64 v68, v60, 0, s[8:9]
	s_cselect_b64 s[8:9], -1, 0
	v_lshlrev_b32_e32 v59, 16, v59
	v_lshlrev_b32_e32 v58, 16, v58
	s_bitcmp0_b32 s28, 5
	v_cndmask_b32_e64 v69, v59, 0, s[8:9]
	v_cndmask_b32_e64 v70, v58, 0, s[8:9]
	s_cselect_b64 s[8:9], -1, 0
	v_lshlrev_b32_e32 v57, 16, v57
	v_lshlrev_b32_e32 v55, 16, v55
	s_bitcmp0_b32 s28, 6
	v_cndmask_b32_e64 v71, v57, 0, s[8:9]
	v_cndmask_b32_e64 v72, v55, 0, s[8:9]
	s_cselect_b64 s[8:9], -1, 0
	v_lshlrev_b32_e32 v55, 16, v56
	v_lshlrev_b32_e32 v53, 16, v53
	s_bitcmp0_b32 s28, 7
	v_cndmask_b32_e64 v59, v55, 0, s[8:9]
	v_cndmask_b32_e64 v60, v53, 0, s[8:9]
	s_cselect_b64 s[8:9], -1, 0
	v_lshlrev_b32_e32 v53, 16, v54
	v_lshlrev_b32_e32 v54, 16, v52
	s_bitcmp0_b32 s28, 8
	v_cndmask_b32_e64 v52, v53, 0, s[8:9]
	v_cndmask_b32_e64 v53, v54, 0, s[8:9]
	s_cselect_b64 s[8:9], -1, 0
	v_lshlrev_b32_e32 v51, 16, v51
	v_lshlrev_b32_e32 v50, 16, v50
	s_bitcmp0_b32 s28, 9
	v_cndmask_b32_e64 v51, v51, 0, s[8:9]
	v_cndmask_b32_e64 v50, v50, 0, s[8:9]
	s_cselect_b64 s[8:9], -1, 0
	v_lshlrev_b32_e32 v49, 16, v49
	v_lshlrev_b32_e32 v9, 16, v9
	s_bitcmp0_b32 s28, 10
	v_cndmask_b32_e64 v54, v49, 0, s[8:9]
	v_cndmask_b32_e64 v49, v9, 0, s[8:9]
	s_cselect_b64 s[8:9], -1, 0
	v_lshlrev_b32_e32 v9, 16, v48
	v_lshlrev_b32_e32 v7, 16, v7
	s_bitcmp0_b32 s28, 11
	v_cndmask_b32_e64 v55, v9, 0, s[8:9]
	v_cndmask_b32_e64 v48, v7, 0, s[8:9]
	s_cselect_b64 s[8:9], -1, 0
	v_lshlrev_b32_e32 v6, 16, v6
	v_cndmask_b32_e64 v56, v6, 0, s[8:9]
.Lmy_ppjoin:
	v_fma_f32 v6, v12, v67, v22
	v_fmac_f32_e32 v6, v20, v65
	v_fmac_f32_e32 v6, v14, v64
	v_fmac_f32_e32 v6, v16, v62
	v_fmac_f32_e32 v6, v18, v69
	v_lshlrev_b32_e32 v7, 16, v8
	v_mul_f32_e32 v8, 0xbfb8aa3b, v6
	v_exp_f32_e32 v8, v8
	v_cndmask_b32_e64 v57, v7, 0, s[8:9]
	v_fma_f32 v7, v13, v66, v23
	v_fmac_f32_e32 v7, v21, v63
	v_add_f32_e32 v8, 1.0, v8
	v_rcp_f32_e32 v8, v8
	v_fmac_f32_e32 v7, v15, v61
	v_fmac_f32_e32 v7, v17, v68
	v_fmac_f32_e32 v7, v19, v70
	v_mul_f32_e32 v6, v6, v8
	v_mul_f32_e32 v8, 0xbfb8aa3b, v7
	v_exp_f32_e32 v8, v8
	v_mul_f32_e32 v6, 0x3e000000, v6
	s_brev_b32 s6, 56
	v_fma_f32 v65, v12, v65, v22
	v_add_f32_e32 v8, 1.0, v8
	v_rcp_f32_e32 v8, v8
	v_cvt_pk_bf16_f32 v66, v6, s0
	v_fmac_f32_e32 v65, v20, v64
	v_fmac_f32_e32 v65, v14, v62
	v_mul_f32_e32 v58, v7, v8
	v_lshl_add_u64 v[8:9], v[2:3], 0, s[0:1]
	v_add_co_u32_e32 v6, vcc, s6, v8
	s_mov_b32 s6, 0x1c088000
	s_nop 0
	v_addc_co_u32_e32 v7, vcc, 0, v9, vcc
	v_add_co_u32_e32 v8, vcc, s6, v8
	v_fmac_f32_e32 v65, v16, v69
	global_store_short v[6:7], v66, off
	v_cvt_pk_bf16_f32 v66, v58, s0
	v_addc_co_u32_e32 v9, vcc, 0, v9, vcc
	v_fmac_f32_e32 v65, v18, v71
	global_store_short v[8:9], v66, off
	v_mul_f32_e32 v66, 0xbfb8aa3b, v65
	v_exp_f32_e32 v66, v66
	v_fma_f32 v63, v13, v63, v23
	v_fmac_f32_e32 v63, v21, v61
	v_fmac_f32_e32 v63, v15, v68
	v_add_f32_e32 v66, 1.0, v66
	v_rcp_f32_e32 v66, v66
	v_fmac_f32_e32 v63, v17, v70
	v_fmac_f32_e32 v63, v19, v72
	v_fma_f32 v64, v12, v64, v22
	v_mul_f32_e32 v65, v65, v66
	v_mul_f32_e32 v66, 0xbfb8aa3b, v63
	v_exp_f32_e32 v66, v66
	v_fmac_f32_e32 v64, v20, v62
	v_mul_f32_e32 v65, 0x3e000000, v65
	v_fmac_f32_e32 v64, v14, v69
	v_add_f32_e32 v66, 1.0, v66
	v_rcp_f32_e32 v66, v66
	v_cvt_pk_bf16_f32 v65, v65, s0
	v_fmac_f32_e32 v64, v16, v71
	global_store_short v[6:7], v65, off offset:128
	v_mul_f32_e32 v63, v63, v66
	v_cvt_pk_bf16_f32 v65, v63, s0
	v_fmac_f32_e32 v64, v18, v59
	global_store_short v[8:9], v65, off offset:128
	v_mul_f32_e32 v65, 0xbfb8aa3b, v64
; __device__ __forceinline__ unsigned pk2(float lo, float hi) { f32x2_t v = {lo, hi}; bf16x2_t b = __builtin_convertvector(v, bf16x2_t); return __builtin_bit_cast(unsigned, b); }
; __device__ __forceinline__ bf16_t f2bf(float f) { return (bf16_t)(pk2(f, 0.f) & 0xffffu); }
; __device__ __forceinline__ float bf2f(unsigned short h) { return __uint_as_float(((unsigned)h) << 16); }
; __device__ __forceinline__ float silu_f(float x) { return x * fast_rcp(1.0f + fast_exp(-x)); }
; __device__ __forceinline__ void mlstm_unit(const Params& p, int l, int b, int h, LAS unsigned char* lds) {
;     ...
; #pragma unroll
;             for (int i = 0; i < 12; ++i) { const bool ok = (ma_ >> i) & 1u; qf[i] = ok ? bf2f(qa_[i]) : 0.f; kf[i] = ok ? bf2f(ka_[i]) : 0.f; }
;             float ko[8];
; #pragma unroll
;             for (int i = 0; i < 8; ++i) { float qv = bq, kv = bk;
; #pragma unroll
;                 for (int jj = 0; jj < 5; ++jj) { qv += wq[jj] * qf[i + jj]; kv += wk[jj] * kf[i + jj]; }
;                 const float qo = silu_f(qv) * 0.125f; ko[i] = silu_f(kv);
;                 QA[(size_t)(tau0 + i) * 64 + lane] = f2bf(qo); KA[(size_t)(tau0 + i) * 64 + lane] = f2bf(ko[i]); }
;             u32x4 kt; kt.x = pk2(ko[0], ko[1]); kt.y = pk2(ko[2], ko[3]); kt.z = pk2(ko[4], ko[5]); kt.w = pk2(ko[6], ko[7]);
;             *(u32x4*)(KAT + (size_t)lane * TK + tau0) = kt;
; #pragma unroll
;             for (int i = 0; i < 12; ++i) { qa_[i] = qb_[i]; ka_[i] = kb_[i]; }
;             ma_ = mb_;
	v_exp_f32_e32 v65, v65
	v_fma_f32 v61, v13, v61, v23
	v_fmac_f32_e32 v61, v21, v68
	v_fmac_f32_e32 v61, v15, v70
	v_add_f32_e32 v65, 1.0, v65
	v_rcp_f32_e32 v65, v65
	v_fmac_f32_e32 v61, v17, v72
	v_fmac_f32_e32 v61, v19, v60
	v_fma_f32 v62, v12, v62, v22
	v_mul_f32_e32 v64, v64, v65
	v_mul_f32_e32 v65, 0xbfb8aa3b, v61
	v_exp_f32_e32 v65, v65
	v_fmac_f32_e32 v62, v20, v69
	v_fmac_f32_e32 v62, v14, v71
	v_fmac_f32_e32 v62, v16, v59
	v_add_f32_e32 v65, 1.0, v65
	v_rcp_f32_e32 v65, v65
	v_fmac_f32_e32 v62, v18, v52
	v_mul_f32_e32 v64, 0x3e000000, v64
	v_cvt_pk_bf16_f32 v64, v64, s0
	v_mul_f32_e32 v61, v61, v65
	v_mul_f32_e32 v65, 0xbfb8aa3b, v62
	v_exp_f32_e32 v65, v65
	global_store_short v[6:7], v64, off offset:256
	v_cvt_pk_bf16_f32 v64, v61, s0
	global_store_short v[8:9], v64, off offset:256
	v_fma_f32 v64, v13, v68, v23
	v_add_f32_e32 v65, 1.0, v65
	v_fmac_f32_e32 v64, v21, v70
	v_rcp_f32_e32 v65, v65
	v_fmac_f32_e32 v64, v15, v72
	v_fmac_f32_e32 v64, v17, v60
	v_fmac_f32_e32 v64, v19, v53
	v_mul_f32_e32 v62, v62, v65
	v_mul_f32_e32 v65, 0xbfb8aa3b, v64
	v_exp_f32_e32 v65, v65
	v_mul_f32_e32 v62, 0x3e000000, v62
	v_cvt_pk_bf16_f32 v62, v62, s0
	global_store_short v[6:7], v62, off offset:384
	v_add_f32_e32 v65, 1.0, v65
	v_rcp_f32_e32 v65, v65
	v_lshl_add_u64 v[2:3], v[2:3], 0, s[30:31]
	s_and_b64 vcc, exec, s[4:5]
	s_mov_b32 s6, s12
	v_mul_f32_e32 v64, v64, v65
	v_cvt_pk_bf16_f32 v62, v64, s0
	global_store_short v[8:9], v62, off offset:384
	v_fma_f32 v62, v12, v69, v22
	v_fmac_f32_e32 v62, v20, v71
	v_fmac_f32_e32 v62, v14, v59
	v_fmac_f32_e32 v62, v16, v52
	v_fmac_f32_e32 v62, v18, v51
	v_mul_f32_e32 v66, 0xbfb8aa3b, v62
	v_exp_f32_e32 v66, v66
	v_fma_f32 v65, v13, v70, v23
	v_fmac_f32_e32 v65, v21, v72
	v_fmac_f32_e32 v65, v15, v60
	v_add_f32_e32 v66, 1.0, v66
	v_rcp_f32_e32 v66, v66
	v_fmac_f32_e32 v65, v17, v53
	v_fmac_f32_e32 v65, v19, v50
	s_mov_b32 s28, s13
	v_mul_f32_e32 v62, v62, v66
	v_mul_f32_e32 v66, 0xbfb8aa3b, v65
	v_exp_f32_e32 v66, v66
	v_mul_f32_e32 v62, 0x3e000000, v62
	v_cvt_pk_bf16_f32 v62, v62, s0
	global_store_short v[6:7], v62, off offset:512
	v_add_f32_e32 v66, 1.0, v66
	v_rcp_f32_e32 v66, v66
	s_nop 0
	v_mul_f32_e32 v65, v65, v66
	v_cvt_pk_bf16_f32 v62, v65, s0
	global_store_short v[8:9], v62, off offset:512
	v_fma_f32 v62, v12, v71, v22
	v_fmac_f32_e32 v62, v20, v59
	v_fmac_f32_e32 v62, v14, v52
	v_fmac_f32_e32 v62, v16, v51
	v_fmac_f32_e32 v62, v18, v54
	v_mul_f32_e32 v67, 0xbfb8aa3b, v62
	v_exp_f32_e32 v67, v67
	v_fma_f32 v66, v13, v72, v23
	v_fmac_f32_e32 v66, v21, v60
	v_fmac_f32_e32 v66, v15, v53
	v_add_f32_e32 v67, 1.0, v67
	v_rcp_f32_e32 v67, v67
	v_fmac_f32_e32 v66, v17, v50
	v_fmac_f32_e32 v66, v19, v49
	v_fma_f32 v59, v12, v59, v22
	v_mul_f32_e32 v62, v62, v67
	v_mul_f32_e32 v67, 0xbfb8aa3b, v66
	v_exp_f32_e32 v67, v67
	v_fmac_f32_e32 v59, v20, v52
	v_mul_f32_e32 v62, 0x3e000000, v62
	v_fmac_f32_e32 v59, v14, v51
	v_add_f32_e32 v67, 1.0, v67
	v_rcp_f32_e32 v67, v67
	v_cvt_pk_bf16_f32 v62, v62, s0
	v_fmac_f32_e32 v59, v16, v54
	global_store_short v[6:7], v62, off offset:640
	v_mul_f32_e32 v66, v66, v67
	v_cvt_pk_bf16_f32 v62, v66, s0
	v_fmac_f32_e32 v59, v18, v55
	global_store_short v[8:9], v62, off offset:640
	v_mul_f32_e32 v62, 0xbfb8aa3b, v59
	v_exp_f32_e32 v62, v62
	v_fma_f32 v52, v12, v52, v22
	v_fma_f32 v60, v13, v60, v23
	v_fmac_f32_e32 v52, v20, v51
	v_fmac_f32_e32 v60, v21, v53
	v_add_f32_e32 v62, 1.0, v62
	v_fma_f32 v53, v13, v53, v23
	v_fmac_f32_e32 v52, v14, v54
	v_fmac_f32_e32 v60, v15, v50
	v_rcp_f32_e32 v62, v62
	v_fmac_f32_e32 v53, v21, v50
	v_fmac_f32_e32 v52, v16, v55
	v_fmac_f32_e32 v60, v17, v49
	v_fmac_f32_e32 v53, v15, v49
	v_fmac_f32_e32 v52, v18, v57
	v_fmac_f32_e32 v60, v19, v48
	v_fmac_f32_e32 v53, v17, v48
	v_mul_f32_e32 v48, 0xbfb8aa3b, v52
	v_fmac_f32_e32 v53, v19, v56
	v_exp_f32_e32 v48, v48
	v_mul_f32_e32 v59, v59, v62
	v_mul_f32_e32 v62, 0xbfb8aa3b, v60
	v_mul_f32_e32 v49, 0xbfb8aa3b, v53
	v_exp_f32_e32 v62, v62
	v_exp_f32_e32 v49, v49
	v_add_f32_e32 v48, 1.0, v48
	v_rcp_f32_e32 v48, v48
	v_add_f32_e32 v62, 1.0, v62
	v_add_f32_e32 v49, 1.0, v49
	v_rcp_f32_e32 v62, v62
	v_rcp_f32_e32 v49, v49
	v_mul_f32_e32 v48, v52, v48
	v_mul_f32_e32 v59, 0x3e000000, v59
	v_mul_f32_e32 v48, 0x3e000000, v48
	v_mul_f32_e32 v60, v60, v62
	v_cvt_pk_bf16_f32 v59, v59, s0
	v_mul_f32_e32 v49, v53, v49
	v_cvt_pk_bf16_f32 v48, v48, s0
	global_store_short v[6:7], v59, off offset:768
	v_cvt_pk_bf16_f32 v59, v60, s0
	global_store_short v[6:7], v48, off offset:896
	v_cvt_pk_bf16_f32 v6, v49, s0
	global_store_short v[8:9], v59, off offset:768
	global_store_short v[8:9], v6, off offset:896
	v_cvt_pk_bf16_f32 v6, v58, v63
	v_cvt_pk_bf16_f32 v7, v61, v64
	v_cvt_pk_bf16_f32 v8, v65, v66
	v_cvt_pk_bf16_f32 v9, v60, v49
	v_lshl_add_u64 v[48:49], v[4:5], 0, s[0:1]
	global_store_dwordx4 v[48:49], v[6:9], off
	v_lshl_add_u64 v[4:5], v[4:5], 0, s[42:43]
	s_waitcnt vmcnt(17)
	v_mov_b32_e32 v66, v24
	v_mov_b32_e32 v63, v26
	v_mov_b32_e32 v61, v28
	v_mov_b32_e32 v60, v30
	v_mov_b32_e32 v58, v32
	v_mov_b32_e32 v55, v34
	v_mov_b32_e32 v53, v36
	v_mov_b32_e32 v52, v38
	v_mov_b32_e32 v50, v40
	v_mov_b32_e32 v9, v42
	v_mov_b32_e32 v7, v44
	v_mov_b32_e32 v6, v46
	v_mov_b32_e32 v67, v25
	v_mov_b32_e32 v65, v27
	v_mov_b32_e32 v64, v29
	v_mov_b32_e32 v62, v31
	v_mov_b32_e32 v59, v33
	v_mov_b32_e32 v57, v35
	v_mov_b32_e32 v56, v37
	v_mov_b32_e32 v54, v39
	v_mov_b32_e32 v51, v41
	v_mov_b32_e32 v49, v43
	v_mov_b32_e32 v48, v45
	v_mov_b32_e32 v8, v47
	s_cbranch_vccnz .LBB0_450
